# P5 modulate loop: each bf16 row's four loads issued together and all gain/shift/scale loads of an iteration hoisted up front (counted waits), on top of v12
# speedup vs baseline: 1.0281x; 1.0132x over previous
; #define GAS __attribute__((address_space(1)))
; DI float bflo(unsigned u) { return __uint_as_float(u << 16); }
; DI float bfhi(unsigned u) { return __uint_as_float(u & 0xffff0000u); }
; template <bool LAT_BF16>
; DI void modulate_phase(const float* xlat, const float* xctx, const float* g, const float* mods_l, bf16_t* h, int tid) {
;     ...
;             for (int j = 0; j < 4; ++j) {
;                 if (LAT_BF16 && rr < MLAT) {
;                     const u32x2 b2 = *(const GAS u32x2*)((const bf16_t*)xlat + (size_t)rr * D + lane * 4 + 256 * j);
;                     v[q][j] = (f32x4){bflo(b2.x), bfhi(b2.x), bflo(b2.y), bfhi(b2.y)};
;                 } else v[q][j] = *(const GAS f32x4*)(src[q] + lane * 4 + 256 * j);
;             }
.LBB0_642:
	s_or_saveexec_b64 s[6:7], s[6:7]
	v_lshlrev_b64 v[62:63], 11, v[8:9]
	v_lshl_add_u64 v[12:13], v[44:45], 0, v[62:63]
	s_xor_b64 exec, exec, s[6:7]
	s_cbranch_execz .LBB0_644
	global_load_dwordx2 v[6:7], v[12:13], off
	global_load_dwordx2 v[100:101], v[12:13], off offset:512
	global_load_dwordx2 v[102:103], v[12:13], off offset:1024
	global_load_dwordx2 v[104:105], v[12:13], off offset:1536
	s_waitcnt vmcnt(3)
	v_lshlrev_b32_e32 v34, 16, v6
	v_and_b32_e32 v35, 0xffff0000, v6
	v_lshlrev_b32_e32 v36, 16, v7
	v_and_b32_e32 v37, 0xffff0000, v7

; #define GAS __attribute__((address_space(1)))
; DI float bflo(unsigned u) { return __uint_as_float(u << 16); }
; DI float bfhi(unsigned u) { return __uint_as_float(u & 0xffff0000u); }
; template <bool LAT_BF16>
; DI void modulate_phase(const float* xlat, const float* xctx, const float* g, const float* mods_l, bf16_t* h, int tid) {
;     ...
;             for (int j = 0; j < 4; ++j) {
;                 if (LAT_BF16 && rr < MLAT) {
;                     const u32x2 b2 = *(const GAS u32x2*)((const bf16_t*)xlat + (size_t)rr * D + lane * 4 + 256 * j);
;                     v[q][j] = (f32x4){bflo(b2.x), bfhi(b2.x), bflo(b2.y), bfhi(b2.y)};
;                 } else v[q][j] = *(const GAS f32x4*)(src[q] + lane * 4 + 256 * j);
;             }
.LBB0_647:
	s_waitcnt vmcnt(2)
	v_lshlrev_b32_e32 v30, 16, v100
	v_and_b32_e32 v31, 0xffff0000, v100
	v_lshlrev_b32_e32 v32, 16, v101
	v_and_b32_e32 v33, 0xffff0000, v101

; #define GAS __attribute__((address_space(1)))
; DI float bflo(unsigned u) { return __uint_as_float(u << 16); }
; DI float bfhi(unsigned u) { return __uint_as_float(u & 0xffff0000u); }
; template <bool LAT_BF16>
; DI void modulate_phase(const float* xlat, const float* xctx, const float* g, const float* mods_l, bf16_t* h, int tid) {
;     ...
;             for (int j = 0; j < 4; ++j) {
;                 if (LAT_BF16 && rr < MLAT) {
;                     const u32x2 b2 = *(const GAS u32x2*)((const bf16_t*)xlat + (size_t)rr * D + lane * 4 + 256 * j);
;                     v[q][j] = (f32x4){bflo(b2.x), bfhi(b2.x), bflo(b2.y), bfhi(b2.y)};
;                 } else v[q][j] = *(const GAS f32x4*)(src[q] + lane * 4 + 256 * j);
;             }
.LBB0_651:
	s_waitcnt vmcnt(1)
	v_lshlrev_b32_e32 v26, 16, v102
	s_waitcnt lgkmcnt(0)
	v_and_b32_e32 v27, 0xffff0000, v102
	v_lshlrev_b32_e32 v28, 16, v103
	v_and_b32_e32 v29, 0xffff0000, v103

; #define GAS __attribute__((address_space(1)))
; DI float bflo(unsigned u) { return __uint_as_float(u << 16); }
; DI float bfhi(unsigned u) { return __uint_as_float(u & 0xffff0000u); }
; template <bool LAT_BF16>
; DI void modulate_phase(const float* xlat, const float* xctx, const float* g, const float* mods_l, bf16_t* h, int tid) {
;     ...
;             for (int j = 0; j < 4; ++j) {
;                 if (LAT_BF16 && rr < MLAT) {
;                     const u32x2 b2 = *(const GAS u32x2*)((const bf16_t*)xlat + (size_t)rr * D + lane * 4 + 256 * j);
;                     v[q][j] = (f32x4){bflo(b2.x), bfhi(b2.x), bflo(b2.y), bfhi(b2.y)};
;                 } else v[q][j] = *(const GAS f32x4*)(src[q] + lane * 4 + 256 * j);
;             }
.LBB0_655:
	s_waitcnt vmcnt(0)
	v_lshlrev_b32_e32 v6, 16, v104
	v_and_b32_e32 v7, 0xffff0000, v104
	v_lshlrev_b32_e32 v8, 16, v105
	v_and_b32_e32 v9, 0xffff0000, v105

; #define GAS __attribute__((address_space(1)))
; DI float bflo(unsigned u) { return __uint_as_float(u << 16); }
; DI float bfhi(unsigned u) { return __uint_as_float(u & 0xffff0000u); }
; template <bool LAT_BF16>
; DI void modulate_phase(const float* xlat, const float* xctx, const float* g, const float* mods_l, bf16_t* h, int tid) {
;     ...
;             for (int j = 0; j < 4; ++j) {
;                 if (LAT_BF16 && rr < MLAT) {
;                     const u32x2 b2 = *(const GAS u32x2*)((const bf16_t*)xlat + (size_t)rr * D + lane * 4 + 256 * j);
;                     v[q][j] = (f32x4){bflo(b2.x), bfhi(b2.x), bflo(b2.y), bfhi(b2.y)};
;                 } else v[q][j] = *(const GAS f32x4*)(src[q] + lane * 4 + 256 * j);
;             }
.LBB0_662:
	s_or_saveexec_b64 s[8:9], s[8:9]
	v_lshlrev_b64 v[14:15], 11, v[14:15]
	v_lshl_add_u64 v[66:67], v[44:45], 0, v[14:15]
	s_xor_b64 exec, exec, s[8:9]
	s_cbranch_execz .LBB0_664
	global_load_dwordx2 v[12:13], v[66:67], off
	global_load_dwordx2 v[106:107], v[66:67], off offset:512
	global_load_dwordx2 v[108:109], v[66:67], off offset:1024
	global_load_dwordx2 v[110:111], v[66:67], off offset:1536
	s_waitcnt vmcnt(3)
	v_lshlrev_b32_e32 v10, 16, v12
	v_and_b32_e32 v11, 0xffff0000, v12
	v_lshlrev_b32_e32 v12, 16, v13
	v_and_b32_e32 v13, 0xffff0000, v13

; #define GAS __attribute__((address_space(1)))
; DI float bflo(unsigned u) { return __uint_as_float(u << 16); }
; DI float bfhi(unsigned u) { return __uint_as_float(u & 0xffff0000u); }
; template <bool LAT_BF16>
; DI void modulate_phase(const float* xlat, const float* xctx, const float* g, const float* mods_l, bf16_t* h, int tid) {
;     ...
;             for (int j = 0; j < 4; ++j) {
;                 if (LAT_BF16 && rr < MLAT) {
;                     const u32x2 b2 = *(const GAS u32x2*)((const bf16_t*)xlat + (size_t)rr * D + lane * 4 + 256 * j);
;                     v[q][j] = (f32x4){bflo(b2.x), bfhi(b2.x), bflo(b2.y), bfhi(b2.y)};
;                 } else v[q][j] = *(const GAS f32x4*)(src[q] + lane * 4 + 256 * j);
;             }
.LBB0_667:
	s_waitcnt vmcnt(2)
	v_lshlrev_b32_e32 v14, 16, v106
	v_and_b32_e32 v15, 0xffff0000, v106
	v_lshlrev_b32_e32 v16, 16, v107
	v_and_b32_e32 v17, 0xffff0000, v107

; #define GAS __attribute__((address_space(1)))
; DI float bflo(unsigned u) { return __uint_as_float(u << 16); }
; DI float bfhi(unsigned u) { return __uint_as_float(u & 0xffff0000u); }
; template <bool LAT_BF16>
; DI void modulate_phase(const float* xlat, const float* xctx, const float* g, const float* mods_l, bf16_t* h, int tid) {
;     ...
;             for (int j = 0; j < 4; ++j) {
;                 if (LAT_BF16 && rr < MLAT) {
;                     const u32x2 b2 = *(const GAS u32x2*)((const bf16_t*)xlat + (size_t)rr * D + lane * 4 + 256 * j);
;                     v[q][j] = (f32x4){bflo(b2.x), bfhi(b2.x), bflo(b2.y), bfhi(b2.y)};
;                 } else v[q][j] = *(const GAS f32x4*)(src[q] + lane * 4 + 256 * j);
;             }
.LBB0_671:
	s_waitcnt vmcnt(1)
	v_lshlrev_b32_e32 v18, 16, v108
	v_and_b32_e32 v19, 0xffff0000, v108
	v_lshlrev_b32_e32 v20, 16, v109
	v_and_b32_e32 v21, 0xffff0000, v109

; #define GAS __attribute__((address_space(1)))
; DI unsigned pk2(float a, float b) { f32x2 v = {a, b}; bf16x2_t r = __builtin_convertvector(v, bf16x2_t); return __builtin_bit_cast(unsigned, r); }
; template <bool LAT_BF16>
; DI void modulate_phase(const float* xlat, const float* xctx, const float* g, const float* mods_l, bf16_t* h, int tid) {
;     ...
; #pragma unroll
;         for (int q = 0; q < 2; ++q) {
;             float ss = 0.f;
; #pragma unroll
;             for (int j = 0; j < 4; ++j) ss += (v[q][j].x * v[q][j].x + v[q][j].y * v[q][j].y) + (v[q][j].z * v[q][j].z + v[q][j].w * v[q][j].w);
;             const float rstd = 1.f / sqrtf(wave_sum(ss) * (1.f / D) + EPS);
;             if (ok[q]) {
; #pragma unroll
;                 for (int j = 0; j < 4; ++j) {
;                     const int k = lane * 4 + 256 * j;
;                     const f32x4 gg = *(const GAS f32x4*)(g + k), sh = *(const GAS f32x4*)(md[q] + k), sc = *(const GAS f32x4*)(md[q] + 1024 + k);
;                     const f32x4 o = (v[q][j] * rstd * gg) * (sc + 1.f) + sh;
;                     u32x2 w; w.x = pk2(o.x, o.y); w.y = pk2(o.z, o.w);
;                     *(GAS u32x2*)(h + (size_t)row[q] * D + k) = w;
;                 }
.LBB0_675:
	s_waitcnt vmcnt(0)
	v_lshlrev_b32_e32 v22, 16, v110
	v_and_b32_e32 v23, 0xffff0000, v110
	v_lshlrev_b32_e32 v24, 16, v111
	v_and_b32_e32 v25, 0xffff0000, v111
.LBB0_676:
	s_or_b64 exec, exec, s[8:9]
	s_waitcnt vmcnt(0)
	v_pk_mul_f32 v[64:65], v[36:37], v[36:37]
	v_pk_mul_f32 v[66:67], v[34:35], v[34:35]
	v_mul_f32_e32 v59, v6, v6
	v_pk_mov_b32 v[80:81], v[66:67], v[64:65] op_sel:[1,0]
	v_mov_b32_e32 v67, v65
	v_pk_add_f32 v[64:65], v[80:81], v[66:67]
	v_pk_mul_f32 v[66:67], v[32:33], v[32:33]
	v_pk_mul_f32 v[80:81], v[30:31], v[30:31]
	v_mul_f32_e32 v61, v7, v7
	v_pk_mov_b32 v[82:83], v[80:81], v[66:67] op_sel:[1,0]
	v_mov_b32_e32 v81, v67
	v_pk_add_f32 v[66:67], v[82:83], v[80:81]
	v_pk_add_f32 v[64:65], v[64:65], v[64:65] op_sel:[0,1] op_sel_hi:[1,0]
	v_pk_add_f32 v[66:67], v[66:67], v[66:67] op_sel:[0,1] op_sel_hi:[1,0]
	v_mov_b32_e32 v65, v59
	v_mov_b32_e32 v67, v61
	v_pk_add_f32 v[88:89], v[64:65], v[66:67]
	s_waitcnt lgkmcnt(0)
	v_mul_f32_e32 v64, v27, v27
	v_mul_f32_e32 v80, v8, v8
	v_pk_fma_f32 v[90:91], v[26:27], v[26:27], v[64:65] op_sel_hi:[1,1,0]
	v_mul_f32_e32 v64, v29, v29
	v_lshl_add_u64 v[94:95], v[2:3], 0, s[24:25]
	v_lshl_add_u64 v[96:97], v[2:3], 0, v[42:43]
	v_mov_b32_e32 v91, v80
	v_pk_fma_f32 v[92:93], v[28:29], v[28:29], v[64:65] op_sel_hi:[1,1,0]
	global_load_dwordx4 v[64:67], v[46:47], off
	v_lshl_add_u64 v[2:3], v[94:95], 0, v[42:43]
	global_load_dwordx4 v[80:83], v[96:97], off
	global_load_dwordx4 v[84:87], v[2:3], off
	global_load_dwordx4 v[112:115], v[46:47], off offset:1024
	v_lshlrev_b32_e32 v116, 2, v48
	v_mov_b32_e32 v117, v43
	v_lshl_add_u64 v[118:119], v[94:95], 0, v[116:117]
	global_load_dwordx4 v[120:123], v[118:119], off
	global_load_dwordx4 v[124:127], v[96:97], off offset:1024
	global_load_dwordx4 v[128:131], v[46:47], off offset:2048
	v_lshlrev_b32_e32 v132, 2, v50
	v_mov_b32_e32 v133, v43
	v_lshl_add_u64 v[134:135], v[94:95], 0, v[132:133]
	global_load_dwordx4 v[136:139], v[134:135], off
	global_load_dwordx4 v[140:143], v[96:97], off offset:2048
	global_load_dwordx4 v[144:147], v[46:47], off offset:3072
	v_lshlrev_b32_e32 v148, 2, v52
	v_mov_b32_e32 v149, v43
	v_lshl_add_u64 v[150:151], v[94:95], 0, v[148:149]
	global_load_dwordx4 v[152:155], v[150:151], off
	global_load_dwordx4 v[156:159], v[96:97], off offset:3072
	v_mul_f32_e32 v98, v9, v9
	v_mov_b32_e32 v93, v98
	v_pk_add_f32 v[2:3], v[90:91], v[92:93]
	s_nop 0
	v_pk_add_f32 v[2:3], v[88:89], v[2:3]
	s_nop 0
	v_add_f32_e32 v2, v2, v3
	ds_bpermute_b32 v3, v74, v2
	s_waitcnt lgkmcnt(0)
	v_add_f32_e32 v2, v2, v3
	ds_bpermute_b32 v3, v75, v2
	s_waitcnt lgkmcnt(0)
	v_add_f32_e32 v2, v2, v3
	ds_bpermute_b32 v3, v76, v2
	s_waitcnt lgkmcnt(0)
	v_add_f32_e32 v2, v2, v3
	ds_bpermute_b32 v3, v77, v2
	s_waitcnt lgkmcnt(0)
	v_add_f32_e32 v2, v2, v3
	ds_bpermute_b32 v3, v78, v2
	s_waitcnt lgkmcnt(0)
	v_add_f32_e32 v2, v2, v3
	ds_bpermute_b32 v3, v79, v2
	s_waitcnt lgkmcnt(0)
	v_add_f32_e32 v2, v2, v3
	v_fmamk_f32 v2, v2, 0x3a800000, v41
	v_mul_f32_e32 v3, 0x4f800000, v2
	v_cmp_gt_f32_e32 vcc, s33, v2
	s_nop 1
	v_cndmask_b32_e32 v2, v2, v3, vcc
	v_sqrt_f32_e32 v3, v2
	s_nop 0
	v_add_u32_e32 v59, -1, v3
	v_add_u32_e32 v61, 1, v3
	v_fma_f32 v88, -v59, v3, v2
	v_fma_f32 v89, -v61, v3, v2
	v_cmp_ge_f32_e64 s[8:9], 0, v88
	s_nop 1
	v_cndmask_b32_e64 v3, v3, v59, s[8:9]
	v_cmp_lt_f32_e64 s[8:9], 0, v89
	s_nop 1
	v_cndmask_b32_e64 v3, v3, v61, s[8:9]
	v_mul_f32_e32 v59, 0x37800000, v3
	v_cndmask_b32_e32 v3, v3, v59, vcc
	v_cmp_class_f32_e32 vcc, v2, v49
	s_nop 1
	v_cndmask_b32_e32 v2, v3, v2, vcc
	v_div_scale_f32 v3, s[8:9], v2, v2, 1.0
	v_rcp_f32_e32 v59, v3
	v_div_scale_f32 v61, vcc, 1.0, v2, 1.0
	v_fma_f32 v88, -v3, v59, 1.0
	v_fmac_f32_e32 v59, v88, v59
	v_mul_f32_e32 v88, v61, v59
	v_fma_f32 v89, -v3, v88, v61
	v_fmac_f32_e32 v88, v89, v59
	v_fma_f32 v3, -v3, v88, v61
	v_div_fmas_f32 v3, v3, v59, v88
	v_div_fixup_f32 v88, v3, v2, 1.0
	v_pk_mul_f32 v[2:3], v[88:89], v[36:37] op_sel_hi:[0,1]
	v_pk_mul_f32 v[34:35], v[88:89], v[34:35] op_sel_hi:[0,1]
	s_waitcnt vmcnt(11)
	v_pk_mul_f32 v[34:35], v[64:65], v[34:35]
	v_pk_mul_f32 v[2:3], v[66:67], v[2:3]
	s_waitcnt vmcnt(9)
	v_pk_add_f32 v[36:37], v[86:87], 1.0 op_sel_hi:[1,0]
	v_pk_add_f32 v[64:65], v[84:85], 1.0 op_sel_hi:[1,0]
	v_pk_fma_f32 v[2:3], v[36:37], v[2:3], v[82:83]
	v_pk_fma_f32 v[34:35], v[64:65], v[34:35], v[80:81]
	v_lshl_add_u64 v[36:37], v[54:55], 0, v[62:63]
	v_cvt_pk_bf16_f32 v34, v34, v35
	v_cvt_pk_bf16_f32 v35, v2, v3
	global_store_dwordx2 v[36:37], v[34:35], off
	v_lshlrev_b32_e32 v2, 2, v48
	v_mov_b32_e32 v3, v43
	v_lshl_add_u64 v[34:35], v[94:95], 0, v[2:3]
	v_pk_mul_f32 v[32:33], v[88:89], v[32:33] op_sel_hi:[0,1]
	v_pk_mul_f32 v[30:31], v[88:89], v[30:31] op_sel_hi:[0,1]
	v_lshlrev_b32_e32 v34, 2, v50
	v_mov_b32_e32 v35, v43
	v_pk_mul_f32 v[28:29], v[88:89], v[28:29] op_sel_hi:[0,1]
	v_pk_mul_f32 v[26:27], v[88:89], v[26:27] op_sel_hi:[0,1]
	v_mul_f32_e32 v59, v23, v23
	v_mul_f32_e32 v61, v25, v25
	v_fmac_f32_e32 v59, v22, v22
	v_fmac_f32_e32 v61, v24, v24
	v_pk_mul_f32 v[8:9], v[88:89], v[8:9] op_sel_hi:[0,1]
	v_pk_mul_f32 v[6:7], v[88:89], v[6:7] op_sel_hi:[0,1]
	s_waitcnt vmcnt(9)
	v_pk_mul_f32 v[30:31], v[112:113], v[30:31]
	v_pk_mul_f32 v[32:33], v[114:115], v[32:33]
	s_waitcnt vmcnt(8)
	v_pk_add_f32 v[62:63], v[122:123], 1.0 op_sel_hi:[1,0]
	v_pk_add_f32 v[64:65], v[120:121], 1.0 op_sel_hi:[1,0]
	s_waitcnt vmcnt(7)
	v_pk_fma_f32 v[32:33], v[62:63], v[32:33], v[126:127]
	v_pk_fma_f32 v[30:31], v[64:65], v[30:31], v[124:125]
	s_nop 0
	v_cvt_pk_bf16_f32 v30, v30, v31
	v_cvt_pk_bf16_f32 v31, v32, v33
	global_store_dwordx2 v[36:37], v[30:31], off offset:512
	v_lshl_add_u64 v[30:31], v[94:95], 0, v[34:35]
	v_lshlrev_b32_e32 v30, 2, v52
	v_mov_b32_e32 v31, v43
	s_waitcnt vmcnt(7)
; #define GAS __attribute__((address_space(1)))
; DI unsigned pk2(float a, float b) { f32x2 v = {a, b}; bf16x2_t r = __builtin_convertvector(v, bf16x2_t); return __builtin_bit_cast(unsigned, r); }
; template <bool LAT_BF16>
; DI void modulate_phase(const float* xlat, const float* xctx, const float* g, const float* mods_l, bf16_t* h, int tid) {
;     ...
; #pragma unroll
;         for (int q = 0; q < 2; ++q) {
;             float ss = 0.f;
; #pragma unroll
;             for (int j = 0; j < 4; ++j) ss += (v[q][j].x * v[q][j].x + v[q][j].y * v[q][j].y) + (v[q][j].z * v[q][j].z + v[q][j].w * v[q][j].w);
;             const float rstd = 1.f / sqrtf(wave_sum(ss) * (1.f / D) + EPS);
;             if (ok[q]) {
; #pragma unroll
;                 for (int j = 0; j < 4; ++j) {
;                     const int k = lane * 4 + 256 * j;
;                     const f32x4 gg = *(const GAS f32x4*)(g + k), sh = *(const GAS f32x4*)(md[q] + k), sc = *(const GAS f32x4*)(md[q] + 1024 + k);
;                     const f32x4 o = (v[q][j] * rstd * gg) * (sc + 1.f) + sh;
;                     u32x2 w; w.x = pk2(o.x, o.y); w.y = pk2(o.z, o.w);
;                     *(GAS u32x2*)(h + (size_t)row[q] * D + k) = w;
;                 }
	v_pk_mul_f32 v[26:27], v[128:129], v[26:27]
	v_pk_mul_f32 v[28:29], v[130:131], v[28:29]
	s_waitcnt vmcnt(6)
	v_pk_add_f32 v[32:33], v[138:139], 1.0 op_sel_hi:[1,0]
	v_pk_add_f32 v[62:63], v[136:137], 1.0 op_sel_hi:[1,0]
	s_waitcnt vmcnt(5)
	v_pk_fma_f32 v[28:29], v[28:29], v[32:33], v[142:143]
	v_pk_fma_f32 v[26:27], v[26:27], v[62:63], v[140:141]
	v_mul_f32_e32 v32, v19, v19
	v_cvt_pk_bf16_f32 v26, v26, v27
	v_cvt_pk_bf16_f32 v27, v28, v29
	global_store_dwordx2 v[36:37], v[26:27], off offset:1024
	v_lshl_add_u64 v[26:27], v[94:95], 0, v[30:31]
	v_mul_f32_e32 v26, v11, v11
	v_mul_f32_e32 v27, v13, v13
	v_mul_f32_e32 v28, v15, v15
	v_mul_f32_e32 v29, v17, v17
	v_mul_f32_e32 v33, v21, v21
	v_fmac_f32_e32 v26, v10, v10
	v_fmac_f32_e32 v27, v12, v12
	v_fmac_f32_e32 v28, v14, v14
	v_fmac_f32_e32 v29, v16, v16
	v_fmac_f32_e32 v32, v18, v18
	v_fmac_f32_e32 v33, v20, v20
	v_add_f32_e32 v26, v26, v27
	v_add_f32_e32 v27, v28, v29
	v_add_f32_e32 v28, v32, v33
	v_add_f32_e32 v26, v26, v27
	v_add_f32_e32 v29, v59, v61
	v_add_f32_e32 v26, v26, v28
	v_add_f32_e32 v26, v26, v29
	ds_bpermute_b32 v27, v74, v26
	s_waitcnt lgkmcnt(0)
	v_add_f32_e32 v26, v26, v27
	ds_bpermute_b32 v27, v75, v26
	s_waitcnt lgkmcnt(0)
	v_add_f32_e32 v26, v26, v27
	ds_bpermute_b32 v27, v76, v26
	s_waitcnt lgkmcnt(0)
	v_add_f32_e32 v26, v26, v27
	ds_bpermute_b32 v27, v77, v26
	s_waitcnt lgkmcnt(0)
	v_add_f32_e32 v26, v26, v27
	ds_bpermute_b32 v27, v78, v26
	s_waitcnt lgkmcnt(0)
	v_add_f32_e32 v26, v26, v27
	ds_bpermute_b32 v27, v79, v26
	s_waitcnt vmcnt(5)
	v_pk_mul_f32 v[6:7], v[6:7], v[144:145]
	v_pk_mul_f32 v[8:9], v[8:9], v[146:147]
	s_waitcnt vmcnt(4)
	v_pk_add_f32 v[28:29], v[154:155], 1.0 op_sel_hi:[1,0]
	v_pk_add_f32 v[32:33], v[152:153], 1.0 op_sel_hi:[1,0]
	s_waitcnt vmcnt(3)
	v_pk_fma_f32 v[8:9], v[8:9], v[28:29], v[158:159]
	v_pk_fma_f32 v[6:7], v[6:7], v[32:33], v[156:157]
	s_nop 0
	v_cvt_pk_bf16_f32 v6, v6, v7
	v_cvt_pk_bf16_f32 v7, v8, v9
	global_store_dwordx2 v[36:37], v[6:7], off offset:1536
	s_and_saveexec_b64 s[8:9], s[6:7]
	s_cbranch_execz .LBB0_635
	v_lshl_add_u64 v[32:33], v[4:5], 0, s[24:25]
	v_lshl_add_u64 v[28:29], v[32:33], 0, v[42:43]
	global_load_dwordx4 v[6:9], v[46:47], off
	global_load_dwordx4 v[62:65], v[28:29], off
	v_lshl_add_u64 v[36:37], v[4:5], 0, v[42:43]
	global_load_dwordx4 v[80:83], v[36:37], off
	global_load_dwordx4 v[160:163], v[46:47], off offset:1024
	v_lshl_add_u64 v[164:165], v[32:33], 0, v[2:3]
	global_load_dwordx4 v[168:171], v[164:165], off
	global_load_dwordx4 v[172:175], v[36:37], off offset:1024
	global_load_dwordx4 v[176:179], v[46:47], off offset:2048
	v_lshl_add_u64 v[166:167], v[32:33], 0, v[34:35]
	global_load_dwordx4 v[180:183], v[166:167], off
	global_load_dwordx4 v[184:187], v[36:37], off offset:2048
	global_load_dwordx4 v[188:191], v[46:47], off offset:3072
	v_lshl_add_u64 v[192:193], v[32:33], 0, v[30:31]
	global_load_dwordx4 v[196:199], v[192:193], off
	global_load_dwordx4 v[204:207], v[36:37], off offset:3072
	s_waitcnt lgkmcnt(0)
	v_add_f32_e32 v4, v26, v27
	v_fmamk_f32 v4, v4, 0x3a800000, v41
	v_mul_f32_e32 v5, 0x4f800000, v4
	v_cmp_gt_f32_e32 vcc, s33, v4
	v_ashrrev_i32_e32 v61, 31, v60
	v_lshl_add_u64 v[2:3], v[32:33], 0, v[2:3]
	v_cndmask_b32_e32 v26, v4, v5, vcc
	v_sqrt_f32_e32 v27, v26
	v_lshlrev_b64 v[4:5], 11, v[60:61]
	v_lshl_add_u64 v[60:61], v[54:55], 0, v[4:5]
	v_add_u32_e32 v28, -1, v27
	v_add_u32_e32 v29, 1, v27
	v_fma_f32 v42, -v28, v27, v26
	v_fma_f32 v59, -v29, v27, v26
	v_cmp_ge_f32_e64 s[6:7], 0, v42
	s_nop 1
	v_cndmask_b32_e64 v27, v27, v28, s[6:7]
	v_cmp_lt_f32_e64 s[6:7], 0, v59
	s_nop 1
	v_cndmask_b32_e64 v27, v27, v29, s[6:7]
	v_mul_f32_e32 v28, 0x37800000, v27
	v_cndmask_b32_e32 v27, v27, v28, vcc
	v_cmp_class_f32_e32 vcc, v26, v49
	s_nop 1
	v_cndmask_b32_e32 v26, v27, v26, vcc
	v_div_scale_f32 v27, s[6:7], v26, v26, 1.0
	v_rcp_f32_e32 v28, v27
	v_div_scale_f32 v4, vcc, 1.0, v26, 1.0
	v_fma_f32 v5, -v27, v28, 1.0
	v_fmac_f32_e32 v28, v5, v28
	v_mul_f32_e32 v5, v4, v28
	v_fma_f32 v29, -v27, v5, v4
	v_fmac_f32_e32 v5, v29, v28
	v_fma_f32 v4, -v27, v5, v4
	v_div_fmas_f32 v4, v4, v28, v5
	v_div_fixup_f32 v42, v4, v26, 1.0
	v_pk_mul_f32 v[4:5], v[42:43], v[12:13] op_sel_hi:[0,1]
	v_pk_mul_f32 v[10:11], v[42:43], v[10:11] op_sel_hi:[0,1]
	v_pk_mul_f32 v[12:13], v[42:43], v[14:15] op_sel_hi:[0,1]
	v_lshl_add_u64 v[14:15], v[32:33], 0, v[34:35]
	s_waitcnt vmcnt(11)
	v_pk_mul_f32 v[6:7], v[10:11], v[6:7]
	v_pk_mul_f32 v[4:5], v[4:5], v[8:9]
	s_waitcnt vmcnt(10)
	v_pk_add_f32 v[8:9], v[64:65], 1.0 op_sel_hi:[1,0]
	v_pk_add_f32 v[10:11], v[62:63], 1.0 op_sel_hi:[1,0]
	s_waitcnt vmcnt(9)
	v_pk_fma_f32 v[4:5], v[4:5], v[8:9], v[82:83]
	v_pk_fma_f32 v[6:7], v[6:7], v[10:11], v[80:81]
	s_nop 0
	v_cvt_pk_bf16_f32 v6, v6, v7
	v_cvt_pk_bf16_f32 v7, v4, v5
	global_store_dwordx2 v[60:61], v[6:7], off
	s_nop 0
	v_pk_mul_f32 v[2:3], v[42:43], v[16:17] op_sel_hi:[0,1]
	v_pk_mul_f32 v[16:17], v[42:43], v[18:19] op_sel_hi:[0,1]
	s_waitcnt vmcnt(8)
	v_pk_add_f32 v[8:9], v[168:169], 1.0 op_sel_hi:[1,0]
	v_pk_mul_f32 v[4:5], v[12:13], v[160:161]
	v_pk_mul_f32 v[2:3], v[2:3], v[162:163]
	v_pk_add_f32 v[6:7], v[170:171], 1.0 op_sel_hi:[1,0]
	s_waitcnt vmcnt(7)
	v_pk_fma_f32 v[4:5], v[4:5], v[8:9], v[172:173]
	v_pk_fma_f32 v[2:3], v[2:3], v[6:7], v[174:175]
	v_cvt_pk_bf16_f32 v4, v4, v5
	v_cvt_pk_bf16_f32 v5, v2, v3
	global_store_dwordx2 v[60:61], v[4:5], off offset:512
	s_nop 0
	v_pk_mul_f32 v[14:15], v[42:43], v[20:21] op_sel_hi:[0,1]
	s_waitcnt vmcnt(6)
	v_pk_add_f32 v[8:9], v[182:183], 1.0 op_sel_hi:[1,0]
	v_pk_mul_f32 v[2:3], v[16:17], v[176:177]
	v_pk_mul_f32 v[4:5], v[14:15], v[178:179]
	v_pk_add_f32 v[6:7], v[180:181], 1.0 op_sel_hi:[1,0]
	s_waitcnt vmcnt(5)
	v_pk_fma_f32 v[4:5], v[4:5], v[8:9], v[186:187]
	v_pk_fma_f32 v[2:3], v[2:3], v[6:7], v[184:185]
	v_lshl_add_u64 v[14:15], v[32:33], 0, v[30:31]
	v_cvt_pk_bf16_f32 v2, v2, v3
	v_cvt_pk_bf16_f32 v3, v4, v5
	global_store_dwordx2 v[60:61], v[2:3], off offset:1024
	s_nop 0
	v_pk_mul_f32 v[14:15], v[42:43], v[24:25] op_sel_hi:[0,1]
	v_pk_mul_f32 v[16:17], v[42:43], v[22:23] op_sel_hi:[0,1]
	s_waitcnt vmcnt(4)
	v_pk_add_f32 v[8:9], v[198:199], 1.0 op_sel_hi:[1,0]
	v_pk_mul_f32 v[2:3], v[16:17], v[188:189]
	v_pk_mul_f32 v[4:5], v[14:15], v[190:191]
	v_pk_add_f32 v[6:7], v[196:197], 1.0 op_sel_hi:[1,0]
	s_waitcnt vmcnt(3)
	v_pk_fma_f32 v[4:5], v[4:5], v[8:9], v[206:207]
	v_pk_fma_f32 v[2:3], v[2:3], v[6:7], v[204:205]
	s_nop 0
	v_cvt_pk_bf16_f32 v2, v2, v3
	v_cvt_pk_bf16_f32 v3, v4, v5
	global_store_dwordx2 v[60:61], v[2:3], off offset:1536
	s_branch .LBB0_635
